# ST1: attention tile loop - waves 4-7 staggered behind waves 0-3 by s_sleep 6 after the per-tile barrier (softmax of one wave under the other's MFMAs); on top of P1
# baseline (speedup 1.0000x reference)
.LBB0_72:
	v_readlane_b32 s4, v251, 9
	s_lshl_b32 s71, s14, 7
	v_readlane_b32 s5, v251, 33
	v_add_u32_e32 v4, s4, v222
	v_add_u32_e32 v6, 0x200, v4
	v_ashrrev_i32_e32 v225, 4, v4
	s_lshl_b32 s4, s14, 8
	v_add_u32_e32 v0, s15, v225
	v_lshlrev_b32_e32 v2, 4, v222
	v_ashrrev_i32_e32 v226, 4, v6
	s_add_u32 s4, s5, s4
	v_readlane_b32 s5, v251, 34
	v_ashrrev_i32_e32 v1, 31, v0
	v_and_b32_e32 v204, 0xf0, v2
	v_add_u32_e32 v2, s15, v226
	s_addc_u32 s5, s5, 0
	v_lshlrev_b64 v[0:1], 10, v[0:1]
	v_ashrrev_i32_e32 v3, 31, v2
	v_lshl_add_u64 v[0:1], s[4:5], 0, v[0:1]
	v_mov_b32_e32 v205, v81
	v_lshlrev_b64 v[2:3], 10, v[2:3]
	v_ashrrev_i32_e32 v224, 3, v4
	v_lshl_add_u64 v[0:1], v[0:1], 0, v[204:205]
	v_lshl_add_u64 v[2:3], s[4:5], 0, v[2:3]
	v_lshl_add_u64 v[2:3], v[2:3], 0, v[204:205]
	global_load_dwordx4 v[130:133], v[0:1], off
	global_load_dwordx4 v[134:137], v[2:3], off
	v_add_u32_e32 v0, s15, v224
	v_ashrrev_i32_e32 v1, 31, v0
	v_readlane_b32 s34, v251, 35
	v_and_b32_e32 v5, 7, v222
	v_lshlrev_b64 v[0:1], 7, v[0:1]
	v_readlane_b32 s35, v251, 36
	v_lshlrev_b32_e32 v206, 4, v5
	v_mov_b32_e32 v207, v81
	v_lshl_add_u64 v[0:1], s[34:35], 0, v[0:1]
	v_ashrrev_i32_e32 v7, 3, v6
	v_lshl_add_u64 v[0:1], v[0:1], 0, v[206:207]
	v_mad_i64_i32 v[208:209], s[14:15], s7, v224, 0
	global_load_dwordx4 v[138:141], v[0:1], off
	v_lshl_add_u64 v[0:1], v[208:209], 1, s[30:31]
	v_mad_i64_i32 v[210:211], s[14:15], s7, v7, 0
	v_lshl_add_u64 v[0:1], v[0:1], 0, v[206:207]
	v_lshl_add_u64 v[2:3], v[210:211], 1, s[30:31]
	v_lshl_add_u64 v[2:3], v[2:3], 0, v[206:207]
	global_load_dwordx4 v[142:145], v[0:1], off
	global_load_dwordx4 v[146:149], v[2:3], off
	v_lshrrev_b32_e32 v1, 6, v4
	v_lshrrev_b32_e32 v2, 3, v4
	v_lshrrev_b32_e32 v3, 4, v4
	v_lshrrev_b32_e32 v8, 5, v4
	v_lshrrev_b32_e32 v4, 2, v4
	v_and_b32_e32 v1, 4, v1
	v_lshlrev_b32_e32 v0, 3, v5
	v_lshrrev_b32_e32 v5, 4, v6
	v_and_b32_e32 v6, 4, v8
	v_and_b32_e32 v4, 24, v4
	v_and_b32_e32 v8, 35, v224
	s_lshr_b32 s81, s7, 6
	v_and_or_b32 v1, v2, 24, v1
	v_or3_b32 v2, v8, v6, v4
	s_cmp_lt_i32 s26, s18
	v_and_or_b32 v3, v3, 35, v1
	s_movk_i32 s7, 0x90
	v_lshl_add_u64 v[214:215], s[4:5], 0, v[204:205]
	v_and_or_b32 v1, v5, 35, v1
	v_mul_u32_u24_e32 v229, 0x190, v2
	s_cselect_b64 s[4:5], -1, 0
	s_sub_i32 s82, s6, s70
	s_lshl_b32 s6, s26, 5
	v_mul_u32_u24_e32 v230, 0x190, v3
	v_mul_lo_u32 v228, v224, s7
	v_lshl_add_u64 v[212:213], s[34:35], 0, v[206:207]
	v_mul_lo_u32 v207, v7, s7
	s_add_i32 s83, s26, 1
	v_mul_u32_u24_e32 v231, 0x190, v1
	v_add3_u32 v1, 0, v229, v206
	v_or_b32_e32 v3, s6, v223
	v_add_lshl_u32 v232, s6, v201, 1
	v_add3_u32 v5, 0, v230, v204
	s_mul_i32 s6, s26, 0x3200
	v_add3_u32 v4, 0, v228, v206
	v_add3_u32 v2, 0, v207, v206
	v_add3_u32 v6, 0, v231, v204
	s_movk_i32 s27, 0x190
	s_cmp_lt_i32 s83, s18
	s_cselect_b64 s[14:15], -1, 0
	v_mov_b32_e32 v32, v81
	v_mov_b32_e32 v33, v81
	v_mov_b32_e32 v46, v81
	v_mov_b32_e32 v47, v81
	v_mul_lo_u32 v233, v3, s27
	v_mov_b32_e32 v34, v81
	v_mov_b32_e32 v35, v81
	v_mov_b32_e32 v36, v81
	s_waitcnt vmcnt(4)
	ds_write_b128 v5, v[130:133]
	s_waitcnt vmcnt(3)
	ds_write_b128 v6, v[134:137]
	s_waitcnt vmcnt(2)
	ds_write_b128 v1, v[138:141] offset:256
	s_waitcnt vmcnt(1)
	ds_write_b128 v4, v[142:145] offset:25600
	s_waitcnt vmcnt(0)
	ds_write_b128 v2, v[146:149] offset:25600
	v_mov_b32_e32 v1, s6
	v_mad_u32_u24 v1, v223, s27, v1
	s_add_i32 s6, 0, 0x3200
	v_add3_u32 v234, v1, v201, s6
	s_lshl_b32 s6, s26, 6
	v_mov_b32_e32 v1, s6
	v_mad_u32_u24 v1, v223, s7, v1
	v_lshlrev_b32_e32 v2, 5, v150
	v_readlane_b32 s6, v255, 37
	v_mov_b32_e32 v37, v81
	v_mov_b32_e32 v38, v81
	v_add3_u32 v235, v1, v2, s6
	v_mov_b32_e32 v39, v81
	v_mov_b32_e32 v40, v81
	v_mov_b32_e32 v41, v81
	v_mov_b32_e32 v42, v81
	v_mov_b32_e32 v43, v81
	v_mov_b32_e32 v44, v81
	v_mov_b32_e32 v45, v81
	v_lshlrev_b32_e32 v80, 1, v0
	v_mov_b64_e32 v[0:1], v[32:33]
	v_mov_b64_e32 v[62:63], v[46:47]
	v_mov_b64_e32 v[16:17], v[32:33]
	v_mul_u32_u24_e32 v227, 0x90, v223
	s_mov_b32 s26, 0
	s_mov_b64 s[6:7], -1
	v_mov_b32_e32 v205, 0
	v_mov_b64_e32 v[2:3], v[34:35]
	v_mov_b64_e32 v[4:5], v[36:37]
	v_mov_b64_e32 v[6:7], v[38:39]
	v_mov_b64_e32 v[8:9], v[40:41]
	v_mov_b64_e32 v[10:11], v[42:43]
	v_mov_b64_e32 v[12:13], v[44:45]
	v_mov_b64_e32 v[14:15], v[46:47]
	v_mov_b64_e32 v[60:61], v[44:45]
	v_mov_b64_e32 v[58:59], v[42:43]
	v_mov_b64_e32 v[56:57], v[40:41]
	v_mov_b64_e32 v[54:55], v[38:39]
	v_mov_b64_e32 v[52:53], v[36:37]
	v_mov_b64_e32 v[50:51], v[34:35]
	v_mov_b64_e32 v[48:49], v[32:33]
	v_mov_b64_e32 v[18:19], v[34:35]
	v_mov_b64_e32 v[20:21], v[36:37]
	v_mov_b64_e32 v[22:23], v[38:39]
	v_mov_b64_e32 v[24:25], v[40:41]
	v_mov_b64_e32 v[26:27], v[42:43]
	v_mov_b64_e32 v[28:29], v[44:45]
	v_mov_b64_e32 v[30:31], v[46:47]
	v_mov_b32_e32 v236, 0
	s_waitcnt lgkmcnt(0)
	s_barrier
	v_readlane_b32 s100, v255, 7
	s_nop 3
	s_cmp_lt_u32 s100, 4
	s_cbranch_scc1 .Latt_nsa
	s_sleep 6
.Latt_nsa:
.LBB0_73:
	s_add_i32 s84, s26, 1
	s_cmp_lt_u32 s84, s81
	s_cselect_b64 s[34:35], -1, 0
	s_cmp_ge_u32 s84, s81
	s_cbranch_scc0 .LBB0_79
	s_andn2_b64 vcc, exec, s[4:5]
	s_cbranch_vccz .LBB0_80

.LBB0_77:
	s_cmp_eq_u32 s84, s81
	s_waitcnt lgkmcnt(0)
	s_barrier
	s_cbranch_scc1 .LBB0_94
	s_mov_b32 s26, s84
	v_readlane_b32 s100, v255, 7
	s_nop 3
	s_cmp_lt_u32 s100, 4
	s_cbranch_scc1 .Latt_nsb
	s_sleep 6
.Latt_nsb:
	s_branch .LBB0_73
.LBB0_79:
	s_lshl_b32 s27, s84, 6
	s_cmp_lt_u32 s27, s70
	s_cselect_b32 s38, s67, s82
	s_add_i32 s38, s38, s27
	v_add_u32_e32 v64, s38, v225
	v_ashrrev_i32_e32 v65, 31, v64
	v_add_u32_e32 v66, s38, v226
	v_lshlrev_b64 v[64:65], 10, v[64:65]
	v_ashrrev_i32_e32 v67, 31, v66
	v_lshl_add_u64 v[64:65], v[214:215], 0, v[64:65]
	v_lshlrev_b64 v[66:67], 10, v[66:67]
	v_lshl_add_u64 v[66:67], v[214:215], 0, v[66:67]
	global_load_dwordx4 v[130:133], v[64:65], off
	global_load_dwordx4 v[134:137], v[66:67], off
	v_add_u32_e32 v64, s38, v224
	v_ashrrev_i32_e32 v65, 31, v64
	s_lshl_b32 s27, s84, 7
	v_lshlrev_b64 v[64:65], 7, v[64:65]
	s_add_u32 s38, s30, s27
	v_lshl_add_u64 v[64:65], v[212:213], 0, v[64:65]
	s_addc_u32 s39, s31, 0
	global_load_dwordx4 v[138:141], v[64:65], off
	v_lshl_add_u64 v[64:65], v[208:209], 1, s[38:39]
	v_lshl_add_u64 v[64:65], v[64:65], 0, v[80:81]
	v_lshl_add_u64 v[66:67], v[210:211], 1, s[38:39]
	v_lshl_add_u64 v[66:67], v[66:67], 0, v[80:81]
	global_load_dwordx4 v[142:145], v[64:65], off
	global_load_dwordx4 v[146:149], v[66:67], off
	s_andn2_b64 vcc, exec, s[4:5]
	s_cbranch_vccnz .LBB0_75
